# phase dispatch: phases made of one hand-written unit branch straight to it and from it to the grid barrier; pure GEMM phases go from the tile loop to the barrier
# speedup vs baseline: 1.0238x; 1.0039x over previous
.LBB0_165:
	s_add_i32 s0, s36, 9
	s_add_u32 s71, s4, 0x3800000
	s_addc_u32 s72, s5, 0
	s_cmp_lt_u32 s0, 21
	v_writelane_b32 v245, s36, 37
	s_cselect_b64 s[0:1], -1, 0
	v_writelane_b32 v245, s0, 38
	s_mov_b32 s24, 0
	s_nop 0
	v_writelane_b32 v245, s1, 39
	s_and_b64 s[0:1], s[0:1], exec
	s_cselect_b32 s7, 0, 0x400
	s_cselect_b32 s100, 1, 0
	s_mov_b32 s101, 0x900
	s_bitcmp1_b32 s101, s36
	s_cselect_b32 s7, 0x400, s7
	s_cmp_eq_u32 s100, 1
	v_writelane_b32 v245, s7, 40
	s_and_b32 s0, s94, 0x15001
	s_cmp_eq_u32 s0, s94
	s_cbranch_scc0 .Lfull_setup
	v_writelane_b32 v247, s70, 28
	v_writelane_b32 v244, s71, 30
	v_writelane_b32 v244, s72, 31
	s_xor_b32 s46, s7, 0x4400
	s_lshr_b32 s47, s7, 8
	v_readlane_b32 s28, v245, 36
	v_readlane_b32 s79, v247, 23
	v_readlane_b32 s78, v247, 22
	v_readlane_b32 s30, v245, 30
	s_mov_b32 s24, s70
	s_mov_b32 s27, s7
	s_bitcmp1_b32 s94, 16
	s_cbranch_scc1 .Ltr_p3
	s_bitcmp1_b32 s94, 14
	s_cbranch_scc1 .Ltr_gn
	s_bitcmp1_b32 s94, 12
	s_cbranch_scc1 .Lss3_entry
	s_bitcmp1_b32 s94, 0
	s_cbranch_scc1 .LBB0_612
	s_branch .Lgemm_skip_state

.Lcg_skip:
	s_and_b32 s0, s94, 56
	v_readlane_b32 s30, v245, 30
	v_readlane_b32 s84, v245, 53
	s_cmp_lg_u32 s0, 0
	v_readlane_b32 s28, v245, 36
	v_readlane_b32 s29, v245, 29
	v_readlane_b32 s31, v245, 31
	s_movk_i32 s80, 0xe00
	s_mov_b32 s33, 0x800000
	s_mov_b32 s81, 0x7f800000
	s_brev_b32 s82, 1
	v_readlane_b32 s85, v245, 54
	s_cbranch_scc0 .Lcg_nosp2
	s_branch .Lcg_sp2
.Lcg_nosp2:
	s_and_b32 s0, s94, 0xfff956f9
	s_cmp_eq_u32 s0, 0
	s_cbranch_scc0 .LBB0_383
	v_readlane_b32 s79, v247, 23
	s_nop 1
	s_branch .Ltr_bar
.Lcg_sp2:
	s_bitcmp1_b32 s94, 3
	v_readlane_b32 s12, v245, 38
	s_cselect_b64 s[0:1], -1, 0
	v_readlane_b32 s13, v245, 39
	s_and_b64 s[0:1], s[12:13], s[0:1]
	s_and_b64 s[0:1], s[0:1], exec
	s_cselect_b32 s10, 0x80, 0
	s_lshl_b32 s0, s94, 3
	s_and_b32 s6, s0, 0x80
	s_and_b32 s7, s94, 32
	s_bfe_i32 s8, s94, 0x10005
	s_and_b64 s[0:1], s[12:13], exec
	s_movk_i32 s0, 0x220
	s_cselect_b32 s0, s0, 0x200
	s_and_b32 s0, s8, s0
	s_add_i32 s11, s10, s6
	s_or_b32 s12, s11, s0
	s_or_b32 s0, s6, s7
	s_cmp_eq_u32 s0, 0
	v_readlane_b32 s0, v246, 1
	s_cselect_b32 s13, s0, s69
	s_cmp_ge_i32 s13, s12
	s_cbranch_scc1 .LBB0_383
	s_add_u32 s20, s4, 0x102000
	s_mul_i32 s14, s70, 0x1f00
	s_addc_u32 s21, s5, 0
	s_add_i32 s15, s14, 0x100
	s_add_i32 s16, s14, 0x200
	s_add_i32 s17, s14, 0x300
	s_add_i32 s18, s14, 0x400
	s_add_i32 s19, s14, 0x500
	s_add_i32 s24, s14, 0x600
	s_add_i32 s25, s14, 0x700
	s_add_i32 s26, s14, 0x800
	s_add_i32 s27, s14, 0x900
	s_add_i32 s46, s14, 0xa00
	s_add_i32 s47, s14, 0xb00
	s_add_i32 s48, s14, 0xc00
	s_add_i32 s49, s14, 0xd00
	s_add_i32 s50, s14, 0xe00
	s_add_i32 s51, s14, 0xf00
	s_add_i32 s52, s14, 0x1000
	s_add_i32 s53, s14, 0x1100
	s_add_i32 s54, s14, 0x1200
	s_add_i32 s55, s14, 0x1300
	s_add_i32 s56, s14, 0x1400
	s_add_i32 s57, s14, 0x1500
	s_add_i32 s58, s14, 0x1600
	s_add_i32 s59, s14, 0x1700
	s_add_i32 s60, s14, 0x1800
	s_add_i32 s61, s14, 0x1900
	s_add_i32 s62, s14, 0x1a00
	s_add_i32 s63, s14, 0x1b00
	s_add_i32 s64, s14, 0x1c00
	s_add_i32 s65, s14, 0x1d00
	s_add_i32 s68, s14, 0x1e00
	s_add_u32 s22, s4, 0x111800
	s_addc_u32 s23, s5, 0
	v_readlane_b32 s0, v244, 23
	v_readlane_b32 s1, v244, 24
	s_add_u32 s0, s4, s0
	s_addc_u32 s1, s5, s1
	s_add_u32 s36, s0, 0x112000
	s_addc_u32 s37, s1, 0
	s_add_u32 s38, s0, 0x112800
	s_addc_u32 s39, s1, 0
	s_add_u32 s40, s4, 0x42000
	s_addc_u32 s41, s5, 0
	s_add_u32 s42, s4, 0x40000
	s_addc_u32 s43, s5, 0
	s_add_u32 s44, s4, 0xac00000
	s_addc_u32 s45, s5, 0
	s_lshl_b32 s69, s13, 5
	s_mov_b32 s78, 0x3a000000
	s_branch .LBB0_347

.Lss3_entry:
	v_readlane_b32 s36, v245, 21
	s_mov_b32 s37, 0

.Lss3_done:
	s_cmp_eq_u32 s94, 0x1000
	s_cbranch_scc0 .LBB0_436
	v_readlane_b32 s79, v247, 23
	s_nop 1
	s_branch .Ltr_bar

.LBB0_610:
	s_and_b32 s0, s12, 7
	s_bfe_u32 s1, s12, 0x10005
	s_lshl_b32 s1, s1, 3
	s_or_b32 s0, s0, s1
	s_bfe_u32 s6, s12, 0x20003
	s_lshr_b32 s8, s12, 6
	v_and_b32_e32 v206, 15, v205
	v_lshrrev_b32_e32 v207, 4, v205
	s_lshl_b32 s7, s8, 8
	s_lshl_b32 s1, s0, 4
	s_add_i32 s7, s7, s1
	s_lshl_b32 s16, s6, 7
	s_add_u32 s16, s16, 0x5e00000
	s_add_u32 s18, s4, s16
	s_addc_u32 s19, s5, 0
	s_mul_i32 s10, s7, 0xe00
	s_add_u32 s20, s18, s10
	s_addc_u32 s21, s19, 0
	v_mul_u32_u24_e32 v208, 0xe00, v206
	v_lshl_add_u32 v208, v207, 4, v208
	global_load_dwordx4 v[128:131], v208, s[20:21] offset:1536
	global_load_dwordx4 v[132:135], v208, s[20:21] offset:1600
	v_lshrrev_b32_e32 v209, 2, v206
	v_and_b32_e32 v210, 3, v206
	v_lshl_add_u32 v209, v209, 3, v210
	v_mul_u32_u24_e32 v209, 0xe00, v209
	v_lshl_add_u32 v209, v207, 4, v209
	s_lshl_b32 s10, s8, 8
	s_mul_i32 s10, s10, 0xe00
	s_add_u32 s24, s18, s10
	s_addc_u32 s25, s19, 0
	global_load_dwordx4 v[64:67], v209, s[24:25] offset:2048
	global_load_dwordx4 v[68:71], v209, s[24:25] offset:2112
	s_add_u32 s24, s24, 0x3800
	s_addc_u32 s25, s25, 0
	global_load_dwordx4 v[72:75], v209, s[24:25] offset:2048
	global_load_dwordx4 v[76:79], v209, s[24:25] offset:2112
	s_add_u32 s24, s24, 0x18800
	s_addc_u32 s25, s25, 0
	global_load_dwordx4 v[80:83], v209, s[24:25] offset:2048
	global_load_dwordx4 v[84:87], v209, s[24:25] offset:2112
	s_add_u32 s24, s24, 0x3800
	s_addc_u32 s25, s25, 0
	global_load_dwordx4 v[88:91], v209, s[24:25] offset:2048
	global_load_dwordx4 v[92:95], v209, s[24:25] offset:2112
	s_add_u32 s24, s24, 0x18800
	s_addc_u32 s25, s25, 0
	global_load_dwordx4 v[96:99], v209, s[24:25] offset:2048
	global_load_dwordx4 v[100:103], v209, s[24:25] offset:2112
	s_add_u32 s24, s24, 0x3800
	s_addc_u32 s25, s25, 0
	global_load_dwordx4 v[104:107], v209, s[24:25] offset:2048
	global_load_dwordx4 v[108:111], v209, s[24:25] offset:2112
	s_add_u32 s24, s24, 0x18800
	s_addc_u32 s25, s25, 0
	global_load_dwordx4 v[112:115], v209, s[24:25] offset:2048
	global_load_dwordx4 v[116:119], v209, s[24:25] offset:2112
	s_add_u32 s24, s24, 0x3800
	s_addc_u32 s25, s25, 0
	global_load_dwordx4 v[120:123], v209, s[24:25] offset:2048
	global_load_dwordx4 v[124:127], v209, s[24:25] offset:2112
	s_add_u32 s24, s24, 0x18800
	s_addc_u32 s25, s25, 0
	v_lshlrev_b32_e32 v210, 9, v206
	v_lshl_add_u32 v210, v207, 4, v210
	s_lshl_b32 s10, s8, 8
	s_lshl_b32 s11, s6, 6
	s_add_i32 s10, s10, s11
	s_lshl_b32 s10, s10, 9
	s_add_u32 s10, s10, 0xa200000
	s_add_u32 s16, s4, s10
	s_addc_u32 s17, s5, 0
	s_add_u32 s22, s16, 0x2000
	s_addc_u32 s23, s17, 0
	s_add_u32 s26, s22, 0x2000
	s_addc_u32 s27, s23, 0
	s_add_u32 s36, s26, 0x2000
	s_addc_u32 s37, s27, 0
	s_mul_i32 s10, s7, 0x600
	s_lshl_b32 s11, s6, 7
	s_add_i32 s10, s10, s11
	s_add_u32 s38, s10, 0xdf00400
	s_waitcnt vmcnt(15)
	v_mfma_f32_16x16x32_bf16 v[0:3], v[64:67], v[128:131], 0
	s_waitcnt vmcnt(14)
	v_mfma_f32_16x16x32_bf16 v[0:3], v[68:71], v[132:135], v[0:3]
	global_load_dwordx4 v[64:67], v209, s[24:25] offset:2048
	global_load_dwordx4 v[68:71], v209, s[24:25] offset:2112
	s_add_u32 s24, s24, 0x3800
	s_addc_u32 s25, s25, 0
	s_waitcnt vmcnt(15)
	v_mfma_f32_16x16x32_bf16 v[4:7], v[72:75], v[128:131], 0
	s_waitcnt vmcnt(14)
	v_mfma_f32_16x16x32_bf16 v[4:7], v[76:79], v[132:135], v[4:7]
	global_load_dwordx4 v[72:75], v209, s[24:25] offset:2048
	global_load_dwordx4 v[76:79], v209, s[24:25] offset:2112
	s_add_u32 s24, s24, 0x18800
	s_addc_u32 s25, s25, 0
	s_waitcnt vmcnt(15)
	v_mfma_f32_16x16x32_bf16 v[8:11], v[80:83], v[128:131], 0
	s_waitcnt vmcnt(14)
	v_mfma_f32_16x16x32_bf16 v[8:11], v[84:87], v[132:135], v[8:11]
	global_load_dwordx4 v[80:83], v209, s[24:25] offset:2048
	global_load_dwordx4 v[84:87], v209, s[24:25] offset:2112
	s_add_u32 s24, s24, 0x3800
	s_addc_u32 s25, s25, 0
	s_waitcnt vmcnt(15)
	v_mfma_f32_16x16x32_bf16 v[12:15], v[88:91], v[128:131], 0
	s_waitcnt vmcnt(14)
	v_mfma_f32_16x16x32_bf16 v[12:15], v[92:95], v[132:135], v[12:15]
	global_load_dwordx4 v[88:91], v209, s[24:25] offset:2048
	global_load_dwordx4 v[92:95], v209, s[24:25] offset:2112
	s_add_u32 s24, s24, 0x18800
	s_addc_u32 s25, s25, 0
	s_waitcnt vmcnt(15)
	v_mfma_f32_16x16x32_bf16 v[16:19], v[96:99], v[128:131], 0
	s_waitcnt vmcnt(14)
	v_mfma_f32_16x16x32_bf16 v[16:19], v[100:103], v[132:135], v[16:19]
	global_load_dwordx4 v[96:99], v209, s[24:25] offset:2048
	global_load_dwordx4 v[100:103], v209, s[24:25] offset:2112
	s_add_u32 s24, s24, 0x3800
	s_addc_u32 s25, s25, 0
	s_waitcnt vmcnt(15)
	v_mfma_f32_16x16x32_bf16 v[20:23], v[104:107], v[128:131], 0
	s_waitcnt vmcnt(14)
	v_mfma_f32_16x16x32_bf16 v[20:23], v[108:111], v[132:135], v[20:23]
	global_load_dwordx4 v[104:107], v209, s[24:25] offset:2048
	global_load_dwordx4 v[108:111], v209, s[24:25] offset:2112
	s_add_u32 s24, s24, 0x18800
	s_addc_u32 s25, s25, 0
	s_waitcnt vmcnt(15)
	v_mfma_f32_16x16x32_bf16 v[24:27], v[112:115], v[128:131], 0
	s_waitcnt vmcnt(14)
	v_mfma_f32_16x16x32_bf16 v[24:27], v[116:119], v[132:135], v[24:27]
	global_load_dwordx4 v[112:115], v209, s[24:25] offset:2048
	global_load_dwordx4 v[116:119], v209, s[24:25] offset:2112
	s_add_u32 s24, s24, 0x3800
	s_addc_u32 s25, s25, 0
	s_waitcnt vmcnt(15)
	v_mfma_f32_16x16x32_bf16 v[28:31], v[120:123], v[128:131], 0
	s_waitcnt vmcnt(14)
	v_mfma_f32_16x16x32_bf16 v[28:31], v[124:127], v[132:135], v[28:31]
	global_load_dwordx4 v[120:123], v209, s[24:25] offset:2048
	global_load_dwordx4 v[124:127], v209, s[24:25] offset:2112
	s_waitcnt vmcnt(15)
	v_mfma_f32_16x16x32_bf16 v[32:35], v[64:67], v[128:131], 0
	s_waitcnt vmcnt(14)
	v_mfma_f32_16x16x32_bf16 v[32:35], v[68:71], v[132:135], v[32:35]
	s_waitcnt vmcnt(13)
	v_mfma_f32_16x16x32_bf16 v[36:39], v[72:75], v[128:131], 0
	s_waitcnt vmcnt(12)
	v_mfma_f32_16x16x32_bf16 v[36:39], v[76:79], v[132:135], v[36:39]
	s_waitcnt vmcnt(11)
	v_mfma_f32_16x16x32_bf16 v[40:43], v[80:83], v[128:131], 0
	s_waitcnt vmcnt(10)
	v_mfma_f32_16x16x32_bf16 v[40:43], v[84:87], v[132:135], v[40:43]
	s_waitcnt vmcnt(9)
	v_mfma_f32_16x16x32_bf16 v[44:47], v[88:91], v[128:131], 0
	s_waitcnt vmcnt(8)
	v_mfma_f32_16x16x32_bf16 v[44:47], v[92:95], v[132:135], v[44:47]
	s_waitcnt vmcnt(7)
	v_mfma_f32_16x16x32_bf16 v[48:51], v[96:99], v[128:131], 0
	s_waitcnt vmcnt(6)
	v_mfma_f32_16x16x32_bf16 v[48:51], v[100:103], v[132:135], v[48:51]
	s_waitcnt vmcnt(5)
	v_mfma_f32_16x16x32_bf16 v[52:55], v[104:107], v[128:131], 0
	s_waitcnt vmcnt(4)
	v_mfma_f32_16x16x32_bf16 v[52:55], v[108:111], v[132:135], v[52:55]
	s_waitcnt vmcnt(3)
	v_mfma_f32_16x16x32_bf16 v[56:59], v[112:115], v[128:131], 0
	s_waitcnt vmcnt(2)
	v_mfma_f32_16x16x32_bf16 v[56:59], v[116:119], v[132:135], v[56:59]
	s_waitcnt vmcnt(1)
	v_mfma_f32_16x16x32_bf16 v[60:63], v[120:123], v[128:131], 0
	s_waitcnt vmcnt(0)
	v_mfma_f32_16x16x32_bf16 v[60:63], v[124:127], v[132:135], v[60:63]
	global_load_dwordx4 v[64:67], v210, s[16:17] offset:0
	global_load_dwordx4 v[68:71], v210, s[22:23] offset:0
	global_load_dwordx4 v[72:75], v210, s[26:27] offset:0
	global_load_dwordx4 v[76:79], v210, s[36:37] offset:0
	global_load_dwordx4 v[80:83], v210, s[16:17] offset:64
	global_load_dwordx4 v[84:87], v210, s[22:23] offset:64
	global_load_dwordx4 v[88:91], v210, s[26:27] offset:64
	global_load_dwordx4 v[92:95], v210, s[36:37] offset:64
	global_load_dwordx4 v[96:99], v210, s[16:17] offset:128
	global_load_dwordx4 v[100:103], v210, s[22:23] offset:128
	global_load_dwordx4 v[104:107], v210, s[26:27] offset:128
	global_load_dwordx4 v[108:111], v210, s[36:37] offset:128
	global_load_dwordx4 v[112:115], v210, s[16:17] offset:192
	global_load_dwordx4 v[116:119], v210, s[22:23] offset:192
	global_load_dwordx4 v[120:123], v210, s[26:27] offset:192
	global_load_dwordx4 v[124:127], v210, s[36:37] offset:192
	s_nop 7
	v_max3_f32 v214, v0, v1, v2
	v_max3_f32 v214, v214, v3, v4
	v_max3_f32 v214, v214, v5, v6
	v_max3_f32 v214, v214, v7, v8
	v_max3_f32 v214, v214, v9, v10
	v_max3_f32 v214, v214, v11, v12
	v_max3_f32 v214, v214, v13, v14
	v_max3_f32 v214, v214, v15, v16
	v_max3_f32 v214, v214, v17, v18
	v_max3_f32 v214, v214, v19, v20
	v_max3_f32 v214, v214, v21, v22
	v_max3_f32 v214, v214, v23, v24
	v_max3_f32 v214, v214, v25, v26
	v_max3_f32 v214, v214, v27, v28
	v_max3_f32 v214, v214, v29, v30
	v_max3_f32 v214, v214, v31, v32
	v_max3_f32 v214, v214, v33, v34
	v_max3_f32 v214, v214, v35, v36
	v_max3_f32 v214, v214, v37, v38
	v_max3_f32 v214, v214, v39, v40
	v_max3_f32 v214, v214, v41, v42
	v_max3_f32 v214, v214, v43, v44
	v_max3_f32 v214, v214, v45, v46
	v_max3_f32 v214, v214, v47, v48
	v_max3_f32 v214, v214, v49, v50
	v_max3_f32 v214, v214, v51, v52
	v_max3_f32 v214, v214, v53, v54
	v_max3_f32 v214, v214, v55, v56
	v_max3_f32 v214, v214, v57, v58
	v_max3_f32 v214, v214, v59, v60
	v_max3_f32 v214, v214, v61, v62
	v_max_f32_e32 v214, v214, v63
	v_xor_b32_e32 v215, 16, v205
	v_lshlrev_b32_e32 v215, 2, v215
	v_xor_b32_e32 v216, 32, v205
	v_lshlrev_b32_e32 v216, 2, v216
	ds_bpermute_b32 v136, v215, v214
	s_waitcnt lgkmcnt(0)
	v_max_f32_e32 v214, v214, v136
	ds_bpermute_b32 v136, v216, v214
	s_waitcnt lgkmcnt(0)
	v_max_f32_e32 v214, v214, v136
	v_mul_f32_e32 v214, 0xbe38aa3b, v214
	s_mov_b32 s10, 0x3e38aa3b
	v_mov_b32_e32 v212, 0
	v_mov_b32_e32 v213, 0
	v_fma_f32 v0, v0, s10, v214
	v_fma_f32 v1, v1, s10, v214
	v_fma_f32 v2, v2, s10, v214
	v_fma_f32 v3, v3, s10, v214
	v_fma_f32 v4, v4, s10, v214
	v_fma_f32 v5, v5, s10, v214
	v_fma_f32 v6, v6, s10, v214
	v_fma_f32 v7, v7, s10, v214
	v_exp_f32_e32 v0, v0
	v_exp_f32_e32 v1, v1
	v_exp_f32_e32 v2, v2
	v_exp_f32_e32 v3, v3
	v_exp_f32_e32 v4, v4
	v_exp_f32_e32 v5, v5
	v_exp_f32_e32 v6, v6
	v_exp_f32_e32 v7, v7
	s_nop 0
	v_add_f32_e32 v212, v212, v0
	v_add_f32_e32 v213, v213, v1
	v_add_f32_e32 v212, v212, v2
	v_add_f32_e32 v213, v213, v3
	v_add_f32_e32 v212, v212, v4
	v_add_f32_e32 v213, v213, v5
	v_add_f32_e32 v212, v212, v6
	v_add_f32_e32 v213, v213, v7
	v_cvt_pk_bf16_f32 v0, v0, v1
	v_cvt_pk_bf16_f32 v1, v2, v3
	v_cvt_pk_bf16_f32 v2, v4, v5
	v_cvt_pk_bf16_f32 v3, v6, v7
	v_fma_f32 v8, v8, s10, v214
	v_fma_f32 v9, v9, s10, v214
	v_fma_f32 v10, v10, s10, v214
	v_fma_f32 v11, v11, s10, v214
	v_fma_f32 v12, v12, s10, v214
	v_fma_f32 v13, v13, s10, v214
	v_fma_f32 v14, v14, s10, v214
	v_fma_f32 v15, v15, s10, v214
	v_exp_f32_e32 v8, v8
	v_exp_f32_e32 v9, v9
	v_exp_f32_e32 v10, v10
	v_exp_f32_e32 v11, v11
	v_exp_f32_e32 v12, v12
	v_exp_f32_e32 v13, v13
	v_exp_f32_e32 v14, v14
	v_exp_f32_e32 v15, v15
	s_nop 0
	v_add_f32_e32 v212, v212, v8
	v_add_f32_e32 v213, v213, v9
	v_add_f32_e32 v212, v212, v10
	v_add_f32_e32 v213, v213, v11
	v_add_f32_e32 v212, v212, v12
	v_add_f32_e32 v213, v213, v13
	v_add_f32_e32 v212, v212, v14
	v_add_f32_e32 v213, v213, v15
	v_cvt_pk_bf16_f32 v8, v8, v9
	v_cvt_pk_bf16_f32 v9, v10, v11
	v_cvt_pk_bf16_f32 v10, v12, v13
	v_cvt_pk_bf16_f32 v11, v14, v15
	v_fma_f32 v16, v16, s10, v214
	v_fma_f32 v17, v17, s10, v214
	v_fma_f32 v18, v18, s10, v214
	v_fma_f32 v19, v19, s10, v214
	v_fma_f32 v20, v20, s10, v214
	v_fma_f32 v21, v21, s10, v214
	v_fma_f32 v22, v22, s10, v214
	v_fma_f32 v23, v23, s10, v214
	v_exp_f32_e32 v16, v16
	v_exp_f32_e32 v17, v17
	v_exp_f32_e32 v18, v18
	v_exp_f32_e32 v19, v19
	v_exp_f32_e32 v20, v20
	v_exp_f32_e32 v21, v21
	v_exp_f32_e32 v22, v22
	v_exp_f32_e32 v23, v23
	s_nop 0
	v_add_f32_e32 v212, v212, v16
	v_add_f32_e32 v213, v213, v17
	v_add_f32_e32 v212, v212, v18
	v_add_f32_e32 v213, v213, v19
	v_add_f32_e32 v212, v212, v20
	v_add_f32_e32 v213, v213, v21
	v_add_f32_e32 v212, v212, v22
	v_add_f32_e32 v213, v213, v23
	v_cvt_pk_bf16_f32 v16, v16, v17
	v_cvt_pk_bf16_f32 v17, v18, v19
	v_cvt_pk_bf16_f32 v18, v20, v21
	v_cvt_pk_bf16_f32 v19, v22, v23
	v_fma_f32 v24, v24, s10, v214
	v_fma_f32 v25, v25, s10, v214
	v_fma_f32 v26, v26, s10, v214
	v_fma_f32 v27, v27, s10, v214
	v_fma_f32 v28, v28, s10, v214
	v_fma_f32 v29, v29, s10, v214
	v_fma_f32 v30, v30, s10, v214
	v_fma_f32 v31, v31, s10, v214
	v_exp_f32_e32 v24, v24
	v_exp_f32_e32 v25, v25
	v_exp_f32_e32 v26, v26
	v_exp_f32_e32 v27, v27
	v_exp_f32_e32 v28, v28
	v_exp_f32_e32 v29, v29
	v_exp_f32_e32 v30, v30
	v_exp_f32_e32 v31, v31
	s_nop 0
	v_add_f32_e32 v212, v212, v24
	v_add_f32_e32 v213, v213, v25
	v_add_f32_e32 v212, v212, v26
	v_add_f32_e32 v213, v213, v27
	v_add_f32_e32 v212, v212, v28
	v_add_f32_e32 v213, v213, v29
	v_add_f32_e32 v212, v212, v30
	v_add_f32_e32 v213, v213, v31
	v_cvt_pk_bf16_f32 v24, v24, v25
	v_cvt_pk_bf16_f32 v25, v26, v27
	v_cvt_pk_bf16_f32 v26, v28, v29
	v_cvt_pk_bf16_f32 v27, v30, v31
	v_fma_f32 v32, v32, s10, v214
	v_fma_f32 v33, v33, s10, v214
	v_fma_f32 v34, v34, s10, v214
	v_fma_f32 v35, v35, s10, v214
	v_fma_f32 v36, v36, s10, v214
	v_fma_f32 v37, v37, s10, v214
	v_fma_f32 v38, v38, s10, v214
	v_fma_f32 v39, v39, s10, v214
	v_exp_f32_e32 v32, v32
	v_exp_f32_e32 v33, v33
	v_exp_f32_e32 v34, v34
	v_exp_f32_e32 v35, v35
	v_exp_f32_e32 v36, v36
	v_exp_f32_e32 v37, v37
	v_exp_f32_e32 v38, v38
	v_exp_f32_e32 v39, v39
	s_nop 0
	v_add_f32_e32 v212, v212, v32
	v_add_f32_e32 v213, v213, v33
	v_add_f32_e32 v212, v212, v34
	v_add_f32_e32 v213, v213, v35
	v_add_f32_e32 v212, v212, v36
	v_add_f32_e32 v213, v213, v37
	v_add_f32_e32 v212, v212, v38
	v_add_f32_e32 v213, v213, v39
	v_cvt_pk_bf16_f32 v32, v32, v33
	v_cvt_pk_bf16_f32 v33, v34, v35
	v_cvt_pk_bf16_f32 v34, v36, v37
	v_cvt_pk_bf16_f32 v35, v38, v39
	v_fma_f32 v40, v40, s10, v214
	v_fma_f32 v41, v41, s10, v214
	v_fma_f32 v42, v42, s10, v214
	v_fma_f32 v43, v43, s10, v214
	v_fma_f32 v44, v44, s10, v214
	v_fma_f32 v45, v45, s10, v214
	v_fma_f32 v46, v46, s10, v214
	v_fma_f32 v47, v47, s10, v214
	v_exp_f32_e32 v40, v40
	v_exp_f32_e32 v41, v41
	v_exp_f32_e32 v42, v42
	v_exp_f32_e32 v43, v43
	v_exp_f32_e32 v44, v44
	v_exp_f32_e32 v45, v45
	v_exp_f32_e32 v46, v46
	v_exp_f32_e32 v47, v47
	s_nop 0
	v_add_f32_e32 v212, v212, v40
	v_add_f32_e32 v213, v213, v41
	v_add_f32_e32 v212, v212, v42
	v_add_f32_e32 v213, v213, v43
	v_add_f32_e32 v212, v212, v44
	v_add_f32_e32 v213, v213, v45
	v_add_f32_e32 v212, v212, v46
	v_add_f32_e32 v213, v213, v47
	v_cvt_pk_bf16_f32 v40, v40, v41
	v_cvt_pk_bf16_f32 v41, v42, v43
	v_cvt_pk_bf16_f32 v42, v44, v45
	v_cvt_pk_bf16_f32 v43, v46, v47
	v_fma_f32 v48, v48, s10, v214
	v_fma_f32 v49, v49, s10, v214
	v_fma_f32 v50, v50, s10, v214
	v_fma_f32 v51, v51, s10, v214
	v_fma_f32 v52, v52, s10, v214
	v_fma_f32 v53, v53, s10, v214
	v_fma_f32 v54, v54, s10, v214
	v_fma_f32 v55, v55, s10, v214
	v_exp_f32_e32 v48, v48
	v_exp_f32_e32 v49, v49
	v_exp_f32_e32 v50, v50
	v_exp_f32_e32 v51, v51
	v_exp_f32_e32 v52, v52
	v_exp_f32_e32 v53, v53
	v_exp_f32_e32 v54, v54
	v_exp_f32_e32 v55, v55
	s_nop 0
	v_add_f32_e32 v212, v212, v48
	v_add_f32_e32 v213, v213, v49
	v_add_f32_e32 v212, v212, v50
	v_add_f32_e32 v213, v213, v51
	v_add_f32_e32 v212, v212, v52
	v_add_f32_e32 v213, v213, v53
	v_add_f32_e32 v212, v212, v54
	v_add_f32_e32 v213, v213, v55
	v_cvt_pk_bf16_f32 v48, v48, v49
	v_cvt_pk_bf16_f32 v49, v50, v51
	v_cvt_pk_bf16_f32 v50, v52, v53
	v_cvt_pk_bf16_f32 v51, v54, v55
	v_fma_f32 v56, v56, s10, v214
	v_fma_f32 v57, v57, s10, v214
	v_fma_f32 v58, v58, s10, v214
	v_fma_f32 v59, v59, s10, v214
	v_fma_f32 v60, v60, s10, v214
	v_fma_f32 v61, v61, s10, v214
	v_fma_f32 v62, v62, s10, v214
	v_fma_f32 v63, v63, s10, v214
	v_exp_f32_e32 v56, v56
	v_exp_f32_e32 v57, v57
	v_exp_f32_e32 v58, v58
	v_exp_f32_e32 v59, v59
	v_exp_f32_e32 v60, v60
	v_exp_f32_e32 v61, v61
	v_exp_f32_e32 v62, v62
	v_exp_f32_e32 v63, v63
	s_nop 0
	v_add_f32_e32 v212, v212, v56
	v_add_f32_e32 v213, v213, v57
	v_add_f32_e32 v212, v212, v58
	v_add_f32_e32 v213, v213, v59
	v_add_f32_e32 v212, v212, v60
	v_add_f32_e32 v213, v213, v61
	v_add_f32_e32 v212, v212, v62
	v_add_f32_e32 v213, v213, v63
	v_cvt_pk_bf16_f32 v56, v56, v57
	v_cvt_pk_bf16_f32 v57, v58, v59
	v_cvt_pk_bf16_f32 v58, v60, v61
	v_cvt_pk_bf16_f32 v59, v62, v63
	v_add_f32_e32 v212, v212, v213
	s_waitcnt vmcnt(15)
	v_mfma_f32_16x16x32_bf16 v[138:141], v[64:67], v[0:3], 0
	global_load_dwordx4 v[64:67], v210, s[16:17] offset:256
	s_waitcnt vmcnt(15)
	v_mfma_f32_16x16x32_bf16 v[142:145], v[68:71], v[0:3], 0
	global_load_dwordx4 v[68:71], v210, s[22:23] offset:256
	s_waitcnt vmcnt(15)
	v_mfma_f32_16x16x32_bf16 v[146:149], v[72:75], v[0:3], 0
	global_load_dwordx4 v[72:75], v210, s[26:27] offset:256
	s_waitcnt vmcnt(15)
	v_mfma_f32_16x16x32_bf16 v[150:153], v[76:79], v[0:3], 0
	global_load_dwordx4 v[76:79], v210, s[36:37] offset:256
	s_waitcnt vmcnt(15)
	v_mfma_f32_16x16x32_bf16 v[138:141], v[80:83], v[8:11], v[138:141]
	global_load_dwordx4 v[80:83], v210, s[16:17] offset:320
	s_waitcnt vmcnt(15)
	v_mfma_f32_16x16x32_bf16 v[142:145], v[84:87], v[8:11], v[142:145]
	global_load_dwordx4 v[84:87], v210, s[22:23] offset:320
	s_waitcnt vmcnt(15)
	v_mfma_f32_16x16x32_bf16 v[146:149], v[88:91], v[8:11], v[146:149]
	global_load_dwordx4 v[88:91], v210, s[26:27] offset:320
	s_waitcnt vmcnt(15)
	v_mfma_f32_16x16x32_bf16 v[150:153], v[92:95], v[8:11], v[150:153]
	global_load_dwordx4 v[92:95], v210, s[36:37] offset:320
	s_waitcnt vmcnt(15)
	v_mfma_f32_16x16x32_bf16 v[138:141], v[96:99], v[16:19], v[138:141]
	global_load_dwordx4 v[96:99], v210, s[16:17] offset:384
	s_waitcnt vmcnt(15)
	v_mfma_f32_16x16x32_bf16 v[142:145], v[100:103], v[16:19], v[142:145]
	global_load_dwordx4 v[100:103], v210, s[22:23] offset:384
	s_waitcnt vmcnt(15)
	v_mfma_f32_16x16x32_bf16 v[146:149], v[104:107], v[16:19], v[146:149]
	global_load_dwordx4 v[104:107], v210, s[26:27] offset:384
	s_waitcnt vmcnt(15)
	v_mfma_f32_16x16x32_bf16 v[150:153], v[108:111], v[16:19], v[150:153]
	global_load_dwordx4 v[108:111], v210, s[36:37] offset:384
	s_waitcnt vmcnt(15)
	v_mfma_f32_16x16x32_bf16 v[138:141], v[112:115], v[24:27], v[138:141]
	global_load_dwordx4 v[112:115], v210, s[16:17] offset:448
	s_waitcnt vmcnt(15)
	v_mfma_f32_16x16x32_bf16 v[142:145], v[116:119], v[24:27], v[142:145]
	global_load_dwordx4 v[116:119], v210, s[22:23] offset:448
	s_waitcnt vmcnt(15)
	v_mfma_f32_16x16x32_bf16 v[146:149], v[120:123], v[24:27], v[146:149]
	global_load_dwordx4 v[120:123], v210, s[26:27] offset:448
	s_waitcnt vmcnt(15)
	v_mfma_f32_16x16x32_bf16 v[150:153], v[124:127], v[24:27], v[150:153]
	global_load_dwordx4 v[124:127], v210, s[36:37] offset:448
	s_waitcnt vmcnt(15)
	v_mfma_f32_16x16x32_bf16 v[138:141], v[64:67], v[32:35], v[138:141]
	s_waitcnt vmcnt(14)
	v_mfma_f32_16x16x32_bf16 v[142:145], v[68:71], v[32:35], v[142:145]
	s_waitcnt vmcnt(13)
	v_mfma_f32_16x16x32_bf16 v[146:149], v[72:75], v[32:35], v[146:149]
	s_waitcnt vmcnt(12)
	v_mfma_f32_16x16x32_bf16 v[150:153], v[76:79], v[32:35], v[150:153]
	s_waitcnt vmcnt(11)
	v_mfma_f32_16x16x32_bf16 v[138:141], v[80:83], v[40:43], v[138:141]
	s_waitcnt vmcnt(10)
	v_mfma_f32_16x16x32_bf16 v[142:145], v[84:87], v[40:43], v[142:145]
	s_waitcnt vmcnt(9)
	v_mfma_f32_16x16x32_bf16 v[146:149], v[88:91], v[40:43], v[146:149]
	s_waitcnt vmcnt(8)
	v_mfma_f32_16x16x32_bf16 v[150:153], v[92:95], v[40:43], v[150:153]
	s_waitcnt vmcnt(7)
	v_mfma_f32_16x16x32_bf16 v[138:141], v[96:99], v[48:51], v[138:141]
	s_waitcnt vmcnt(6)
	v_mfma_f32_16x16x32_bf16 v[142:145], v[100:103], v[48:51], v[142:145]
	s_waitcnt vmcnt(5)
	v_mfma_f32_16x16x32_bf16 v[146:149], v[104:107], v[48:51], v[146:149]
	s_waitcnt vmcnt(4)
	v_mfma_f32_16x16x32_bf16 v[150:153], v[108:111], v[48:51], v[150:153]
	s_waitcnt vmcnt(3)
	v_mfma_f32_16x16x32_bf16 v[138:141], v[112:115], v[56:59], v[138:141]
	s_waitcnt vmcnt(2)
	v_mfma_f32_16x16x32_bf16 v[142:145], v[116:119], v[56:59], v[142:145]
	s_waitcnt vmcnt(1)
	v_mfma_f32_16x16x32_bf16 v[146:149], v[120:123], v[56:59], v[146:149]
	s_waitcnt vmcnt(0)
	v_mfma_f32_16x16x32_bf16 v[150:153], v[124:127], v[56:59], v[150:153]
	ds_bpermute_b32 v136, v215, v212
	s_waitcnt lgkmcnt(0)
	v_add_f32_e32 v212, v212, v136
	ds_bpermute_b32 v136, v216, v212
	s_waitcnt lgkmcnt(0)
	v_add_f32_e32 v212, v212, v136
	v_rcp_f32_e32 v213, v212
	s_nop 0
	v_fma_f32 v136, -v212, v213, 1.0
	v_fma_f32 v213, v136, v213, v213
	v_mul_u32_u24_e32 v208, 0x600, v206
	v_lshl_add_u32 v208, v207, 3, v208
	s_add_u32 s10, s4, s38
	s_addc_u32 s11, s5, 0
	s_nop 2
	v_mul_f32_e32 v138, v138, v213
	v_mul_f32_e32 v139, v139, v213
	v_mul_f32_e32 v140, v140, v213
	v_mul_f32_e32 v141, v141, v213
	v_cvt_pk_bf16_f32 v138, v138, v139
	v_cvt_pk_bf16_f32 v139, v140, v141
	global_store_dwordx2 v208, v[138:139], s[10:11] offset:0
	v_mul_f32_e32 v142, v142, v213
	v_mul_f32_e32 v143, v143, v213
	v_mul_f32_e32 v144, v144, v213
	v_mul_f32_e32 v145, v145, v213
	v_cvt_pk_bf16_f32 v142, v142, v143
	v_cvt_pk_bf16_f32 v143, v144, v145
	global_store_dwordx2 v208, v[142:143], s[10:11] offset:32
	v_mul_f32_e32 v146, v146, v213
	v_mul_f32_e32 v147, v147, v213
	v_mul_f32_e32 v148, v148, v213
	v_mul_f32_e32 v149, v149, v213
	v_cvt_pk_bf16_f32 v146, v146, v147
	v_cvt_pk_bf16_f32 v147, v148, v149
	global_store_dwordx2 v208, v[146:147], s[10:11] offset:64
	v_mul_f32_e32 v150, v150, v213
	v_mul_f32_e32 v151, v151, v213
	v_mul_f32_e32 v152, v152, v213
	v_mul_f32_e32 v153, v153, v213
	v_cvt_pk_bf16_f32 v150, v150, v151
	v_cvt_pk_bf16_f32 v151, v152, v153
	global_store_dwordx2 v208, v[150:151], s[10:11] offset:96
	s_branch .LBB0_443
.Ltr_gn:
	s_branch .Lgn_entry
.Ltr_p3:
	s_branch .Lp3_entry
.Ltr_bar:
	s_branch .LBB0_632
.LBB0_611:
	s_mov_b64 s[2:3], 0x15fb20
	s_mov_b64 s[64:65], 0x400

.Lrn_p1_end:
	s_cmp_eq_u32 s94, 1
	s_cbranch_scc1 .LBB0_632

.Lgn_entry:
	v_and_b32_e32 v206, 15, v205
	v_lshrrev_b32_e32 v207, 4, v205
	v_lshlrev_b32_e32 v208, 3, v205
	v_lshlrev_b32_e32 v209, 4, v205
	v_lshrrev_b32_e32 v210, 6, v186
	s_nop 0
	v_readfirstlane_b32 s22, v210
	v_lshrrev_b32_e32 v135, 3, v205
	v_and_b32_e32 v132, 7, v205
	v_xor_b32_e32 v132, v132, v135
	v_lshlrev_b32_e32 v132, 4, v132
	v_lshl_add_u32 v132, v135, 9, v132
	s_lshl_b32 s23, s22, 13
	v_and_b32_e32 v135, 7, v206
	v_xor_b32_e32 v133, 0, v207
	v_xor_b32_e32 v133, v133, v135
	v_lshlrev_b32_e32 v133, 4, v133
	v_lshl_add_u32 v133, v206, 7, v133
	v_add_u32_e32 v128, 0x10000, v133
	v_add_u32_e32 v133, s23, v133
	v_xor_b32_e32 v134, 4, v207
	v_or_b32_e32 v134, 4, v207
	v_xor_b32_e32 v134, v134, v135
	v_lshlrev_b32_e32 v134, 4, v134
	v_lshl_add_u32 v134, v206, 7, v134
	v_add_u32_e32 v129, 0x10000, v134
	v_add_u32_e32 v134, s23, v134
	v_mul_u32_u24_e32 v212, 0x90, v206
	v_add_u32_e32 v212, 0x21000, v212
	v_lshl_add_u32 v211, v210, 2, v207
	v_lshl_add_u32 v211, v211, 2, v212
	v_lshlrev_b32_e32 v213, 11, v206
	v_lshl_add_u32 v213, v207, 3, v213
	s_lshl_b32 s0, s22, 6
	s_addk_i32 s0, 0x600
	v_add_u32_e32 v213, s0, v213
	s_mul_i32 s0, s24, 0x1600000
	s_add_u32 s0, s0, 0xfc0000
	s_lshl_b32 s1, s22, 14
	s_add_u32 s0, s0, s1
	s_add_u32 s8, s4, s0
	s_addc_u32 s9, s5, 0
	s_lshl_b32 s16, s69, 6
	s_addk_i32 s16, 0x400
	s_mov_b32 s17, 0

.Lp3_entry:
	v_lshlrev_b32_e32 v0, 4, v205
	v_lshlrev_b32_e32 v1, 3, v205
	v_readlane_b32 s0, v245, 21
	v_readlane_b32 s6, v247, 29
	v_readlane_b32 s7, v247, 30
	s_add_u32 s8, s4, 0x3800000
	s_addc_u32 s9, s5, 0
	s_lshl_b32 s1, s0, 15
	s_add_u32 s6, s6, s1
	s_addc_u32 s7, s7, 0
	s_lshl_b32 s1, s0, 12
	s_add_u32 s8, s8, s1
	s_addc_u32 s9, s9, 0
	s_lshl_b32 s1, s0, 14
	s_add_u32 s1, s1, 0x3e00000
	s_add_u32 s10, s4, s1
	s_addc_u32 s11, s5, 0
	s_lshl_b32 s1, s0, 11
	s_add_u32 s1, s1, 0x3c00000
	s_add_u32 s12, s4, s1
	s_addc_u32 s13, s5, 0
	s_lshl_b32 s1, s24, 12
	s_add_u32 s1, s1, 0x225320
	s_add_u32 s14, s4, s1
	s_addc_u32 s15, s5, 0
	s_mul_i32 s1, s24, 0x1e000
	s_add_u32 s16, s4, s1
	s_addc_u32 s17, s5, 0
	s_lshr_b32 s1, s0, 9
	s_mul_i32 s1, s1, 0x6000
	s_add_u32 s1, s1, 0x3000
	s_add_u32 s18, s16, s1
	s_addc_u32 s19, s17, 0
	s_add_u32 s16, s16, 0x1b000
	s_addc_u32 s17, s17, 0
	s_cmp_lt_u32 s0, 0x400
	s_cselect_b32 s1, 1, 0
	s_cmp_eq_u32 s27, 0
	s_cselect_b32 s1, s1, 0
	s_cmp_eq_u32 s1, 1
	s_cbranch_scc0 .Lrn_p3_noctx
	global_load_dwordx4 v[2:5], v0, s[14:15] offset:0
	global_load_dwordx4 v[6:9], v0, s[14:15] offset:1024
	global_load_dwordx4 v[10:13], v0, s[14:15] offset:2048
	global_load_dwordx4 v[14:17], v0, s[14:15] offset:3072
	s_add_u32 s20, s16, 0x1000
	s_addc_u32 s21, s17, 0
	global_load_dwordx4 v[18:21], v0, s[20:21] offset:0
	global_load_dwordx4 v[22:25], v0, s[20:21] offset:1024
	global_load_dwordx4 v[26:29], v0, s[20:21] offset:2048
	global_load_dwordx4 v[30:33], v0, s[20:21] offset:3072
	global_load_dwordx4 v[34:37], v0, s[16:17] offset:0
	global_load_dwordx4 v[38:41], v0, s[16:17] offset:1024
	global_load_dwordx4 v[42:45], v0, s[16:17] offset:2048
	global_load_dwordx4 v[46:49], v0, s[16:17] offset:3072
	global_load_dwordx4 v[82:85], v0, s[8:9] offset:0
	global_load_dwordx4 v[86:89], v0, s[8:9] offset:1024
	global_load_dwordx4 v[90:93], v0, s[8:9] offset:2048
	global_load_dwordx4 v[94:97], v0, s[8:9] offset:3072
	s_add_u32 s20, s18, 0x1000
	s_addc_u32 s21, s19, 0
	global_load_dwordx4 v[50:53], v0, s[20:21] offset:0
	global_load_dwordx4 v[54:57], v0, s[20:21] offset:1024
	global_load_dwordx4 v[58:61], v0, s[20:21] offset:2048
	global_load_dwordx4 v[62:65], v0, s[20:21] offset:3072
	global_load_dwordx4 v[66:69], v0, s[18:19] offset:0
	global_load_dwordx4 v[70:73], v0, s[18:19] offset:1024
	global_load_dwordx4 v[74:77], v0, s[18:19] offset:2048
	global_load_dwordx4 v[78:81], v0, s[18:19] offset:3072
	global_load_dwordx4 v[98:101], v0, s[6:7] offset:0
	global_load_dwordx4 v[102:105], v0, s[6:7] offset:1024
	global_load_dwordx4 v[106:109], v0, s[6:7] offset:2048
	global_load_dwordx4 v[110:113], v0, s[6:7] offset:3072
	s_add_u32 s6, s6, 0x1000
	s_addc_u32 s7, s7, 0
	global_load_dwordx4 v[114:117], v0, s[6:7] offset:0
	global_load_dwordx4 v[118:121], v0, s[6:7] offset:1024
	global_load_dwordx4 v[122:125], v0, s[6:7] offset:2048
	global_load_dwordx4 v[126:129], v0, s[6:7] offset:3072
	s_add_u32 s6, s6, 0x1000
	s_addc_u32 s7, s7, 0
	global_load_dwordx4 v[138:141], v0, s[6:7] offset:0
	global_load_dwordx4 v[142:145], v0, s[6:7] offset:1024
	global_load_dwordx4 v[146:149], v0, s[6:7] offset:2048
	global_load_dwordx4 v[150:153], v0, s[6:7] offset:3072
	s_add_u32 s6, s6, 0x1000
	s_addc_u32 s7, s7, 0
	global_load_dwordx4 v[154:157], v0, s[6:7] offset:0
	global_load_dwordx4 v[158:161], v0, s[6:7] offset:1024
	global_load_dwordx4 v[162:165], v0, s[6:7] offset:2048
	global_load_dwordx4 v[166:169], v0, s[6:7] offset:3072
	s_add_u32 s6, s6, 0x1000
	s_addc_u32 s7, s7, 0
	global_load_dwordx4 v[170:173], v0, s[6:7] offset:0
	global_load_dwordx4 v[174:177], v0, s[6:7] offset:1024
	global_load_dwordx4 v[178:181], v0, s[6:7] offset:2048
	global_load_dwordx4 v[182:185], v0, s[6:7] offset:3072
	s_add_u32 s6, s6, 0x1000
	s_addc_u32 s7, s7, 0
	s_waitcnt vmcnt(28)
	v_pk_mul_f32 v[130:131], v[82:83], v[82:83]
	v_pk_fma_f32 v[130:131], v[84:85], v[84:85], v[130:131]
	v_pk_fma_f32 v[130:131], v[86:87], v[86:87], v[130:131]
	v_pk_fma_f32 v[130:131], v[88:89], v[88:89], v[130:131]
	v_pk_fma_f32 v[130:131], v[90:91], v[90:91], v[130:131]
	v_pk_fma_f32 v[130:131], v[92:93], v[92:93], v[130:131]
	v_pk_fma_f32 v[130:131], v[94:95], v[94:95], v[130:131]
	v_pk_fma_f32 v[130:131], v[96:97], v[96:97], v[130:131]
	v_add_f32_e32 v130, v130, v131
	s_nop 1
	v_add_f32_dpp v130, v130, v130 row_ror:8 row_mask:0xf bank_mask:0xf
	s_nop 1
	v_add_f32_dpp v130, v130, v130 row_ror:4 row_mask:0xf bank_mask:0xf
	s_nop 1
	v_add_f32_dpp v130, v130, v130 row_ror:2 row_mask:0xf bank_mask:0xf
	s_nop 1
	v_add_f32_dpp v130, v130, v130 row_ror:1 row_mask:0xf bank_mask:0xf
	s_nop 1
	s_nop 0
	v_readlane_b32 s0, v130, 0
	v_readlane_b32 s1, v130, 16
	v_readlane_b32 s22, v130, 32
	v_readlane_b32 s23, v130, 48
	s_nop 1
	v_mov_b32_e32 v132, s0
	v_add_f32_e32 v132, s1, v132
	v_add_f32_e32 v132, s22, v132
	v_add_f32_e32 v132, s23, v132
	v_fmamk_f32 v132, v132, 0x3a800000, v197
	v_rsq_f32_e32 v132, v132
	s_nop 0
	v_pk_add_f32 v[18:19], v[18:19], 1.0 op_sel_hi:[1,0]
	v_pk_add_f32 v[20:21], v[20:21], 1.0 op_sel_hi:[1,0]
	v_pk_add_f32 v[22:23], v[22:23], 1.0 op_sel_hi:[1,0]
	v_pk_add_f32 v[24:25], v[24:25], 1.0 op_sel_hi:[1,0]
	v_pk_add_f32 v[26:27], v[26:27], 1.0 op_sel_hi:[1,0]
	v_pk_add_f32 v[28:29], v[28:29], 1.0 op_sel_hi:[1,0]
	v_pk_add_f32 v[30:31], v[30:31], 1.0 op_sel_hi:[1,0]
	v_pk_add_f32 v[32:33], v[32:33], 1.0 op_sel_hi:[1,0]
	v_pk_mul_f32 v[82:83], v[82:83], v[132:133] op_sel_hi:[1,0]
	v_pk_mul_f32 v[84:85], v[84:85], v[132:133] op_sel_hi:[1,0]
	v_pk_mul_f32 v[86:87], v[86:87], v[132:133] op_sel_hi:[1,0]
	v_pk_mul_f32 v[88:89], v[88:89], v[132:133] op_sel_hi:[1,0]
	v_pk_mul_f32 v[90:91], v[90:91], v[132:133] op_sel_hi:[1,0]
	v_pk_mul_f32 v[92:93], v[92:93], v[132:133] op_sel_hi:[1,0]
	v_pk_mul_f32 v[94:95], v[94:95], v[132:133] op_sel_hi:[1,0]
	v_pk_mul_f32 v[96:97], v[96:97], v[132:133] op_sel_hi:[1,0]
	v_pk_mul_f32 v[82:83], v[2:3], v[82:83]
	v_pk_mul_f32 v[84:85], v[4:5], v[84:85]
	v_pk_mul_f32 v[86:87], v[6:7], v[86:87]
	v_pk_mul_f32 v[88:89], v[8:9], v[88:89]
	v_pk_mul_f32 v[90:91], v[10:11], v[90:91]
	v_pk_mul_f32 v[92:93], v[12:13], v[92:93]
	v_pk_mul_f32 v[94:95], v[14:15], v[94:95]
	v_pk_mul_f32 v[96:97], v[16:17], v[96:97]
	v_pk_fma_f32 v[82:83], v[18:19], v[82:83], v[34:35]
	v_pk_fma_f32 v[84:85], v[20:21], v[84:85], v[36:37]
	v_pk_fma_f32 v[86:87], v[22:23], v[86:87], v[38:39]
	v_pk_fma_f32 v[88:89], v[24:25], v[88:89], v[40:41]
	v_pk_fma_f32 v[90:91], v[26:27], v[90:91], v[42:43]
	v_pk_fma_f32 v[92:93], v[28:29], v[92:93], v[44:45]
	v_pk_fma_f32 v[94:95], v[30:31], v[94:95], v[46:47]
	v_pk_fma_f32 v[96:97], v[32:33], v[96:97], v[48:49]
	v_cvt_pk_bf16_f32 v82, v82, v83
	v_cvt_pk_bf16_f32 v83, v84, v85
	v_cvt_pk_bf16_f32 v84, v86, v87
	v_cvt_pk_bf16_f32 v85, v88, v89
	v_cvt_pk_bf16_f32 v86, v90, v91
	v_cvt_pk_bf16_f32 v87, v92, v93
	v_cvt_pk_bf16_f32 v88, v94, v95
	v_cvt_pk_bf16_f32 v89, v96, v97
	global_store_dwordx2 v1, v[82:83], s[12:13] offset:0
	global_store_dwordx2 v1, v[84:85], s[12:13] offset:512
	global_store_dwordx2 v1, v[86:87], s[12:13] offset:1024
	global_store_dwordx2 v1, v[88:89], s[12:13] offset:1536
	global_load_dwordx4 v[82:85], v0, s[6:7] offset:0
	global_load_dwordx4 v[86:89], v0, s[6:7] offset:1024
	global_load_dwordx4 v[90:93], v0, s[6:7] offset:2048
	global_load_dwordx4 v[94:97], v0, s[6:7] offset:3072
	s_add_u32 s6, s6, 0x1000
	s_addc_u32 s7, s7, 0
	s_waitcnt vmcnt(24)
	v_pk_mul_f32 v[130:131], v[98:99], v[98:99]
	v_pk_fma_f32 v[130:131], v[100:101], v[100:101], v[130:131]
	v_pk_fma_f32 v[130:131], v[102:103], v[102:103], v[130:131]
	v_pk_fma_f32 v[130:131], v[104:105], v[104:105], v[130:131]
	v_pk_fma_f32 v[130:131], v[106:107], v[106:107], v[130:131]
	v_pk_fma_f32 v[130:131], v[108:109], v[108:109], v[130:131]
	v_pk_fma_f32 v[130:131], v[110:111], v[110:111], v[130:131]
	v_pk_fma_f32 v[130:131], v[112:113], v[112:113], v[130:131]
	v_add_f32_e32 v130, v130, v131
	s_nop 1
	v_add_f32_dpp v130, v130, v130 row_ror:8 row_mask:0xf bank_mask:0xf
	s_nop 1
	v_add_f32_dpp v130, v130, v130 row_ror:4 row_mask:0xf bank_mask:0xf
	s_nop 1
	v_add_f32_dpp v130, v130, v130 row_ror:2 row_mask:0xf bank_mask:0xf
	s_nop 1
	v_add_f32_dpp v130, v130, v130 row_ror:1 row_mask:0xf bank_mask:0xf
	s_nop 1
	s_nop 0
	v_readlane_b32 s0, v130, 0
	v_readlane_b32 s1, v130, 16
	v_readlane_b32 s22, v130, 32
	v_readlane_b32 s23, v130, 48
	s_nop 1
	v_mov_b32_e32 v132, s0
	v_add_f32_e32 v132, s1, v132
	v_add_f32_e32 v132, s22, v132
	v_add_f32_e32 v132, s23, v132
	v_fmamk_f32 v132, v132, 0x3a800000, v197
	v_rsq_f32_e32 v132, v132
	s_nop 0
	v_pk_add_f32 v[50:51], v[50:51], 1.0 op_sel_hi:[1,0]
	v_pk_add_f32 v[52:53], v[52:53], 1.0 op_sel_hi:[1,0]
	v_pk_add_f32 v[54:55], v[54:55], 1.0 op_sel_hi:[1,0]
	v_pk_add_f32 v[56:57], v[56:57], 1.0 op_sel_hi:[1,0]
	v_pk_add_f32 v[58:59], v[58:59], 1.0 op_sel_hi:[1,0]
	v_pk_add_f32 v[60:61], v[60:61], 1.0 op_sel_hi:[1,0]
	v_pk_add_f32 v[62:63], v[62:63], 1.0 op_sel_hi:[1,0]
	v_pk_add_f32 v[64:65], v[64:65], 1.0 op_sel_hi:[1,0]
	v_pk_mul_f32 v[98:99], v[98:99], v[132:133] op_sel_hi:[1,0]
	v_pk_mul_f32 v[100:101], v[100:101], v[132:133] op_sel_hi:[1,0]
	v_pk_mul_f32 v[102:103], v[102:103], v[132:133] op_sel_hi:[1,0]
	v_pk_mul_f32 v[104:105], v[104:105], v[132:133] op_sel_hi:[1,0]
	v_pk_mul_f32 v[106:107], v[106:107], v[132:133] op_sel_hi:[1,0]
	v_pk_mul_f32 v[108:109], v[108:109], v[132:133] op_sel_hi:[1,0]
	v_pk_mul_f32 v[110:111], v[110:111], v[132:133] op_sel_hi:[1,0]
	v_pk_mul_f32 v[112:113], v[112:113], v[132:133] op_sel_hi:[1,0]
	v_pk_mul_f32 v[98:99], v[2:3], v[98:99]
	v_pk_mul_f32 v[100:101], v[4:5], v[100:101]
	v_pk_mul_f32 v[102:103], v[6:7], v[102:103]
	v_pk_mul_f32 v[104:105], v[8:9], v[104:105]
	v_pk_mul_f32 v[106:107], v[10:11], v[106:107]
	v_pk_mul_f32 v[108:109], v[12:13], v[108:109]
	v_pk_mul_f32 v[110:111], v[14:15], v[110:111]
	v_pk_mul_f32 v[112:113], v[16:17], v[112:113]
	v_pk_fma_f32 v[98:99], v[50:51], v[98:99], v[66:67]
	v_pk_fma_f32 v[100:101], v[52:53], v[100:101], v[68:69]
	v_pk_fma_f32 v[102:103], v[54:55], v[102:103], v[70:71]
	v_pk_fma_f32 v[104:105], v[56:57], v[104:105], v[72:73]
	v_pk_fma_f32 v[106:107], v[58:59], v[106:107], v[74:75]
	v_pk_fma_f32 v[108:109], v[60:61], v[108:109], v[76:77]
	v_pk_fma_f32 v[110:111], v[62:63], v[110:111], v[78:79]
	v_pk_fma_f32 v[112:113], v[64:65], v[112:113], v[80:81]
	v_cvt_pk_bf16_f32 v98, v98, v99
	v_cvt_pk_bf16_f32 v99, v100, v101
	v_cvt_pk_bf16_f32 v100, v102, v103
	v_cvt_pk_bf16_f32 v101, v104, v105
	v_cvt_pk_bf16_f32 v102, v106, v107
	v_cvt_pk_bf16_f32 v103, v108, v109
	v_cvt_pk_bf16_f32 v104, v110, v111
	v_cvt_pk_bf16_f32 v105, v112, v113
	global_store_dwordx2 v1, v[98:99], s[10:11] offset:0
	global_store_dwordx2 v1, v[100:101], s[10:11] offset:512
	global_store_dwordx2 v1, v[102:103], s[10:11] offset:1024
	global_store_dwordx2 v1, v[104:105], s[10:11] offset:1536
	s_add_u32 s10, s10, 0x800
	s_addc_u32 s11, s11, 0
	global_load_dwordx4 v[98:101], v0, s[6:7] offset:0
	global_load_dwordx4 v[102:105], v0, s[6:7] offset:1024
	global_load_dwordx4 v[106:109], v0, s[6:7] offset:2048
	global_load_dwordx4 v[110:113], v0, s[6:7] offset:3072
	s_add_u32 s6, s6, 0x1000
	s_addc_u32 s7, s7, 0
	s_waitcnt vmcnt(28)
	v_pk_mul_f32 v[130:131], v[114:115], v[114:115]
	v_pk_fma_f32 v[130:131], v[116:117], v[116:117], v[130:131]
	v_pk_fma_f32 v[130:131], v[118:119], v[118:119], v[130:131]
	v_pk_fma_f32 v[130:131], v[120:121], v[120:121], v[130:131]
	v_pk_fma_f32 v[130:131], v[122:123], v[122:123], v[130:131]
	v_pk_fma_f32 v[130:131], v[124:125], v[124:125], v[130:131]
	v_pk_fma_f32 v[130:131], v[126:127], v[126:127], v[130:131]
	v_pk_fma_f32 v[130:131], v[128:129], v[128:129], v[130:131]
	v_add_f32_e32 v130, v130, v131
	s_nop 1
	v_add_f32_dpp v130, v130, v130 row_ror:8 row_mask:0xf bank_mask:0xf
	s_nop 1
	v_add_f32_dpp v130, v130, v130 row_ror:4 row_mask:0xf bank_mask:0xf
	s_nop 1
	v_add_f32_dpp v130, v130, v130 row_ror:2 row_mask:0xf bank_mask:0xf
	s_nop 1
	v_add_f32_dpp v130, v130, v130 row_ror:1 row_mask:0xf bank_mask:0xf
	s_nop 1
	s_nop 0
	v_readlane_b32 s0, v130, 0
	v_readlane_b32 s1, v130, 16
	v_readlane_b32 s22, v130, 32
	v_readlane_b32 s23, v130, 48
	s_nop 1
	v_mov_b32_e32 v132, s0
	v_add_f32_e32 v132, s1, v132
	v_add_f32_e32 v132, s22, v132
	v_add_f32_e32 v132, s23, v132
	v_fmamk_f32 v132, v132, 0x3a800000, v197
	v_rsq_f32_e32 v132, v132
	s_nop 0
	v_pk_mul_f32 v[114:115], v[114:115], v[132:133] op_sel_hi:[1,0]
	v_pk_mul_f32 v[116:117], v[116:117], v[132:133] op_sel_hi:[1,0]
	v_pk_mul_f32 v[118:119], v[118:119], v[132:133] op_sel_hi:[1,0]
	v_pk_mul_f32 v[120:121], v[120:121], v[132:133] op_sel_hi:[1,0]
	v_pk_mul_f32 v[122:123], v[122:123], v[132:133] op_sel_hi:[1,0]
	v_pk_mul_f32 v[124:125], v[124:125], v[132:133] op_sel_hi:[1,0]
	v_pk_mul_f32 v[126:127], v[126:127], v[132:133] op_sel_hi:[1,0]
	v_pk_mul_f32 v[128:129], v[128:129], v[132:133] op_sel_hi:[1,0]
	v_pk_mul_f32 v[114:115], v[2:3], v[114:115]
	v_pk_mul_f32 v[116:117], v[4:5], v[116:117]
	v_pk_mul_f32 v[118:119], v[6:7], v[118:119]
	v_pk_mul_f32 v[120:121], v[8:9], v[120:121]
	v_pk_mul_f32 v[122:123], v[10:11], v[122:123]
	v_pk_mul_f32 v[124:125], v[12:13], v[124:125]
	v_pk_mul_f32 v[126:127], v[14:15], v[126:127]
	v_pk_mul_f32 v[128:129], v[16:17], v[128:129]
	v_pk_fma_f32 v[114:115], v[50:51], v[114:115], v[66:67]
	v_pk_fma_f32 v[116:117], v[52:53], v[116:117], v[68:69]
	v_pk_fma_f32 v[118:119], v[54:55], v[118:119], v[70:71]
	v_pk_fma_f32 v[120:121], v[56:57], v[120:121], v[72:73]
	v_pk_fma_f32 v[122:123], v[58:59], v[122:123], v[74:75]
	v_pk_fma_f32 v[124:125], v[60:61], v[124:125], v[76:77]
	v_pk_fma_f32 v[126:127], v[62:63], v[126:127], v[78:79]
	v_pk_fma_f32 v[128:129], v[64:65], v[128:129], v[80:81]
	v_cvt_pk_bf16_f32 v114, v114, v115
	v_cvt_pk_bf16_f32 v115, v116, v117
	v_cvt_pk_bf16_f32 v116, v118, v119
	v_cvt_pk_bf16_f32 v117, v120, v121
	v_cvt_pk_bf16_f32 v118, v122, v123
	v_cvt_pk_bf16_f32 v119, v124, v125
	v_cvt_pk_bf16_f32 v120, v126, v127
	v_cvt_pk_bf16_f32 v121, v128, v129
	global_store_dwordx2 v1, v[114:115], s[10:11] offset:0
	global_store_dwordx2 v1, v[116:117], s[10:11] offset:512
	global_store_dwordx2 v1, v[118:119], s[10:11] offset:1024
	global_store_dwordx2 v1, v[120:121], s[10:11] offset:1536
	s_add_u32 s10, s10, 0x800
	s_addc_u32 s11, s11, 0
	global_load_dwordx4 v[114:117], v0, s[6:7] offset:0
	global_load_dwordx4 v[118:121], v0, s[6:7] offset:1024
	global_load_dwordx4 v[122:125], v0, s[6:7] offset:2048
	global_load_dwordx4 v[126:129], v0, s[6:7] offset:3072
	s_waitcnt vmcnt(32)
	v_pk_mul_f32 v[130:131], v[138:139], v[138:139]
	v_pk_fma_f32 v[130:131], v[140:141], v[140:141], v[130:131]
	v_pk_fma_f32 v[130:131], v[142:143], v[142:143], v[130:131]
	v_pk_fma_f32 v[130:131], v[144:145], v[144:145], v[130:131]
	v_pk_fma_f32 v[130:131], v[146:147], v[146:147], v[130:131]
	v_pk_fma_f32 v[130:131], v[148:149], v[148:149], v[130:131]
	v_pk_fma_f32 v[130:131], v[150:151], v[150:151], v[130:131]
	v_pk_fma_f32 v[130:131], v[152:153], v[152:153], v[130:131]
	v_add_f32_e32 v130, v130, v131
	s_nop 1
	v_add_f32_dpp v130, v130, v130 row_ror:8 row_mask:0xf bank_mask:0xf
	s_nop 1
	v_add_f32_dpp v130, v130, v130 row_ror:4 row_mask:0xf bank_mask:0xf
	s_nop 1
	v_add_f32_dpp v130, v130, v130 row_ror:2 row_mask:0xf bank_mask:0xf
	s_nop 1
	v_add_f32_dpp v130, v130, v130 row_ror:1 row_mask:0xf bank_mask:0xf
	s_nop 1
	s_nop 0
	v_readlane_b32 s0, v130, 0
	v_readlane_b32 s1, v130, 16
	v_readlane_b32 s22, v130, 32
	v_readlane_b32 s23, v130, 48
	s_nop 1
	v_mov_b32_e32 v132, s0
	v_add_f32_e32 v132, s1, v132
	v_add_f32_e32 v132, s22, v132
	v_add_f32_e32 v132, s23, v132
	v_fmamk_f32 v132, v132, 0x3a800000, v197
	v_rsq_f32_e32 v132, v132
	s_nop 0
	v_pk_mul_f32 v[138:139], v[138:139], v[132:133] op_sel_hi:[1,0]
	v_pk_mul_f32 v[140:141], v[140:141], v[132:133] op_sel_hi:[1,0]
	v_pk_mul_f32 v[142:143], v[142:143], v[132:133] op_sel_hi:[1,0]
	v_pk_mul_f32 v[144:145], v[144:145], v[132:133] op_sel_hi:[1,0]
	v_pk_mul_f32 v[146:147], v[146:147], v[132:133] op_sel_hi:[1,0]
	v_pk_mul_f32 v[148:149], v[148:149], v[132:133] op_sel_hi:[1,0]
	v_pk_mul_f32 v[150:151], v[150:151], v[132:133] op_sel_hi:[1,0]
	v_pk_mul_f32 v[152:153], v[152:153], v[132:133] op_sel_hi:[1,0]
	v_pk_mul_f32 v[138:139], v[2:3], v[138:139]
	v_pk_mul_f32 v[140:141], v[4:5], v[140:141]
	v_pk_mul_f32 v[142:143], v[6:7], v[142:143]
	v_pk_mul_f32 v[144:145], v[8:9], v[144:145]
	v_pk_mul_f32 v[146:147], v[10:11], v[146:147]
	v_pk_mul_f32 v[148:149], v[12:13], v[148:149]
	v_pk_mul_f32 v[150:151], v[14:15], v[150:151]
	v_pk_mul_f32 v[152:153], v[16:17], v[152:153]
	v_pk_fma_f32 v[138:139], v[50:51], v[138:139], v[66:67]
	v_pk_fma_f32 v[140:141], v[52:53], v[140:141], v[68:69]
	v_pk_fma_f32 v[142:143], v[54:55], v[142:143], v[70:71]
	v_pk_fma_f32 v[144:145], v[56:57], v[144:145], v[72:73]
	v_pk_fma_f32 v[146:147], v[58:59], v[146:147], v[74:75]
	v_pk_fma_f32 v[148:149], v[60:61], v[148:149], v[76:77]
	v_pk_fma_f32 v[150:151], v[62:63], v[150:151], v[78:79]
	v_pk_fma_f32 v[152:153], v[64:65], v[152:153], v[80:81]
	v_cvt_pk_bf16_f32 v138, v138, v139
	v_cvt_pk_bf16_f32 v139, v140, v141
	v_cvt_pk_bf16_f32 v140, v142, v143
	v_cvt_pk_bf16_f32 v141, v144, v145
	v_cvt_pk_bf16_f32 v142, v146, v147
	v_cvt_pk_bf16_f32 v143, v148, v149
	v_cvt_pk_bf16_f32 v144, v150, v151
	v_cvt_pk_bf16_f32 v145, v152, v153
	global_store_dwordx2 v1, v[138:139], s[10:11] offset:0
	global_store_dwordx2 v1, v[140:141], s[10:11] offset:512
	global_store_dwordx2 v1, v[142:143], s[10:11] offset:1024
	global_store_dwordx2 v1, v[144:145], s[10:11] offset:1536
	s_add_u32 s10, s10, 0x800
	s_addc_u32 s11, s11, 0
	s_waitcnt vmcnt(32)
	v_pk_mul_f32 v[130:131], v[154:155], v[154:155]
	v_pk_fma_f32 v[130:131], v[156:157], v[156:157], v[130:131]
	v_pk_fma_f32 v[130:131], v[158:159], v[158:159], v[130:131]
	v_pk_fma_f32 v[130:131], v[160:161], v[160:161], v[130:131]
	v_pk_fma_f32 v[130:131], v[162:163], v[162:163], v[130:131]
	v_pk_fma_f32 v[130:131], v[164:165], v[164:165], v[130:131]
	v_pk_fma_f32 v[130:131], v[166:167], v[166:167], v[130:131]
	v_pk_fma_f32 v[130:131], v[168:169], v[168:169], v[130:131]
	v_add_f32_e32 v130, v130, v131
	s_nop 1
	v_add_f32_dpp v130, v130, v130 row_ror:8 row_mask:0xf bank_mask:0xf
	s_nop 1
	v_add_f32_dpp v130, v130, v130 row_ror:4 row_mask:0xf bank_mask:0xf
	s_nop 1
	v_add_f32_dpp v130, v130, v130 row_ror:2 row_mask:0xf bank_mask:0xf
	s_nop 1
	v_add_f32_dpp v130, v130, v130 row_ror:1 row_mask:0xf bank_mask:0xf
	s_nop 1
	s_nop 0
	v_readlane_b32 s0, v130, 0
	v_readlane_b32 s1, v130, 16
	v_readlane_b32 s22, v130, 32
	v_readlane_b32 s23, v130, 48
	s_nop 1
	v_mov_b32_e32 v132, s0
	v_add_f32_e32 v132, s1, v132
	v_add_f32_e32 v132, s22, v132
	v_add_f32_e32 v132, s23, v132
	v_fmamk_f32 v132, v132, 0x3a800000, v197
	v_rsq_f32_e32 v132, v132
	s_nop 0
	v_pk_mul_f32 v[154:155], v[154:155], v[132:133] op_sel_hi:[1,0]
	v_pk_mul_f32 v[156:157], v[156:157], v[132:133] op_sel_hi:[1,0]
	v_pk_mul_f32 v[158:159], v[158:159], v[132:133] op_sel_hi:[1,0]
	v_pk_mul_f32 v[160:161], v[160:161], v[132:133] op_sel_hi:[1,0]
	v_pk_mul_f32 v[162:163], v[162:163], v[132:133] op_sel_hi:[1,0]
	v_pk_mul_f32 v[164:165], v[164:165], v[132:133] op_sel_hi:[1,0]
	v_pk_mul_f32 v[166:167], v[166:167], v[132:133] op_sel_hi:[1,0]
	v_pk_mul_f32 v[168:169], v[168:169], v[132:133] op_sel_hi:[1,0]
	v_pk_mul_f32 v[154:155], v[2:3], v[154:155]
	v_pk_mul_f32 v[156:157], v[4:5], v[156:157]
	v_pk_mul_f32 v[158:159], v[6:7], v[158:159]
	v_pk_mul_f32 v[160:161], v[8:9], v[160:161]
	v_pk_mul_f32 v[162:163], v[10:11], v[162:163]
	v_pk_mul_f32 v[164:165], v[12:13], v[164:165]
	v_pk_mul_f32 v[166:167], v[14:15], v[166:167]
	v_pk_mul_f32 v[168:169], v[16:17], v[168:169]
	v_pk_fma_f32 v[154:155], v[50:51], v[154:155], v[66:67]
	v_pk_fma_f32 v[156:157], v[52:53], v[156:157], v[68:69]
	v_pk_fma_f32 v[158:159], v[54:55], v[158:159], v[70:71]
	v_pk_fma_f32 v[160:161], v[56:57], v[160:161], v[72:73]
	v_pk_fma_f32 v[162:163], v[58:59], v[162:163], v[74:75]
	v_pk_fma_f32 v[164:165], v[60:61], v[164:165], v[76:77]
	v_pk_fma_f32 v[166:167], v[62:63], v[166:167], v[78:79]
	v_pk_fma_f32 v[168:169], v[64:65], v[168:169], v[80:81]
	v_cvt_pk_bf16_f32 v154, v154, v155
	v_cvt_pk_bf16_f32 v155, v156, v157
	v_cvt_pk_bf16_f32 v156, v158, v159
	v_cvt_pk_bf16_f32 v157, v160, v161
	v_cvt_pk_bf16_f32 v158, v162, v163
	v_cvt_pk_bf16_f32 v159, v164, v165
	v_cvt_pk_bf16_f32 v160, v166, v167
	v_cvt_pk_bf16_f32 v161, v168, v169
	global_store_dwordx2 v1, v[154:155], s[10:11] offset:0
	global_store_dwordx2 v1, v[156:157], s[10:11] offset:512
	global_store_dwordx2 v1, v[158:159], s[10:11] offset:1024
	global_store_dwordx2 v1, v[160:161], s[10:11] offset:1536
	s_add_u32 s10, s10, 0x800
	s_addc_u32 s11, s11, 0
	s_waitcnt vmcnt(32)
	v_pk_mul_f32 v[130:131], v[170:171], v[170:171]
	v_pk_fma_f32 v[130:131], v[172:173], v[172:173], v[130:131]
	v_pk_fma_f32 v[130:131], v[174:175], v[174:175], v[130:131]
	v_pk_fma_f32 v[130:131], v[176:177], v[176:177], v[130:131]
	v_pk_fma_f32 v[130:131], v[178:179], v[178:179], v[130:131]
	v_pk_fma_f32 v[130:131], v[180:181], v[180:181], v[130:131]
	v_pk_fma_f32 v[130:131], v[182:183], v[182:183], v[130:131]
	v_pk_fma_f32 v[130:131], v[184:185], v[184:185], v[130:131]
	v_add_f32_e32 v130, v130, v131
	s_nop 1
	v_add_f32_dpp v130, v130, v130 row_ror:8 row_mask:0xf bank_mask:0xf
	s_nop 1
	v_add_f32_dpp v130, v130, v130 row_ror:4 row_mask:0xf bank_mask:0xf
	s_nop 1
	v_add_f32_dpp v130, v130, v130 row_ror:2 row_mask:0xf bank_mask:0xf
	s_nop 1
	v_add_f32_dpp v130, v130, v130 row_ror:1 row_mask:0xf bank_mask:0xf
	s_nop 1
	s_nop 0
	v_readlane_b32 s0, v130, 0
	v_readlane_b32 s1, v130, 16
	v_readlane_b32 s22, v130, 32
	v_readlane_b32 s23, v130, 48
	s_nop 1
	v_mov_b32_e32 v132, s0
	v_add_f32_e32 v132, s1, v132
	v_add_f32_e32 v132, s22, v132
	v_add_f32_e32 v132, s23, v132
	v_fmamk_f32 v132, v132, 0x3a800000, v197
	v_rsq_f32_e32 v132, v132
	s_nop 0
	v_pk_mul_f32 v[170:171], v[170:171], v[132:133] op_sel_hi:[1,0]
	v_pk_mul_f32 v[172:173], v[172:173], v[132:133] op_sel_hi:[1,0]
	v_pk_mul_f32 v[174:175], v[174:175], v[132:133] op_sel_hi:[1,0]
	v_pk_mul_f32 v[176:177], v[176:177], v[132:133] op_sel_hi:[1,0]
	v_pk_mul_f32 v[178:179], v[178:179], v[132:133] op_sel_hi:[1,0]
	v_pk_mul_f32 v[180:181], v[180:181], v[132:133] op_sel_hi:[1,0]
	v_pk_mul_f32 v[182:183], v[182:183], v[132:133] op_sel_hi:[1,0]
	v_pk_mul_f32 v[184:185], v[184:185], v[132:133] op_sel_hi:[1,0]
	v_pk_mul_f32 v[170:171], v[2:3], v[170:171]
	v_pk_mul_f32 v[172:173], v[4:5], v[172:173]
	v_pk_mul_f32 v[174:175], v[6:7], v[174:175]
	v_pk_mul_f32 v[176:177], v[8:9], v[176:177]
	v_pk_mul_f32 v[178:179], v[10:11], v[178:179]
	v_pk_mul_f32 v[180:181], v[12:13], v[180:181]
	v_pk_mul_f32 v[182:183], v[14:15], v[182:183]
	v_pk_mul_f32 v[184:185], v[16:17], v[184:185]
	v_pk_fma_f32 v[170:171], v[50:51], v[170:171], v[66:67]
	v_pk_fma_f32 v[172:173], v[52:53], v[172:173], v[68:69]
	v_pk_fma_f32 v[174:175], v[54:55], v[174:175], v[70:71]
	v_pk_fma_f32 v[176:177], v[56:57], v[176:177], v[72:73]
	v_pk_fma_f32 v[178:179], v[58:59], v[178:179], v[74:75]
	v_pk_fma_f32 v[180:181], v[60:61], v[180:181], v[76:77]
	v_pk_fma_f32 v[182:183], v[62:63], v[182:183], v[78:79]
	v_pk_fma_f32 v[184:185], v[64:65], v[184:185], v[80:81]
	v_cvt_pk_bf16_f32 v170, v170, v171
	v_cvt_pk_bf16_f32 v171, v172, v173
	v_cvt_pk_bf16_f32 v172, v174, v175
	v_cvt_pk_bf16_f32 v173, v176, v177
	v_cvt_pk_bf16_f32 v174, v178, v179
	v_cvt_pk_bf16_f32 v175, v180, v181
	v_cvt_pk_bf16_f32 v176, v182, v183
	v_cvt_pk_bf16_f32 v177, v184, v185
	global_store_dwordx2 v1, v[170:171], s[10:11] offset:0
	global_store_dwordx2 v1, v[172:173], s[10:11] offset:512
	global_store_dwordx2 v1, v[174:175], s[10:11] offset:1024
	global_store_dwordx2 v1, v[176:177], s[10:11] offset:1536
	s_add_u32 s10, s10, 0x800
	s_addc_u32 s11, s11, 0
	s_waitcnt vmcnt(28)
	v_pk_mul_f32 v[130:131], v[82:83], v[82:83]
	v_pk_fma_f32 v[130:131], v[84:85], v[84:85], v[130:131]
	v_pk_fma_f32 v[130:131], v[86:87], v[86:87], v[130:131]
	v_pk_fma_f32 v[130:131], v[88:89], v[88:89], v[130:131]
	v_pk_fma_f32 v[130:131], v[90:91], v[90:91], v[130:131]
	v_pk_fma_f32 v[130:131], v[92:93], v[92:93], v[130:131]
	v_pk_fma_f32 v[130:131], v[94:95], v[94:95], v[130:131]
	v_pk_fma_f32 v[130:131], v[96:97], v[96:97], v[130:131]
	v_add_f32_e32 v130, v130, v131
	s_nop 1
	v_add_f32_dpp v130, v130, v130 row_ror:8 row_mask:0xf bank_mask:0xf
	s_nop 1
	v_add_f32_dpp v130, v130, v130 row_ror:4 row_mask:0xf bank_mask:0xf
	s_nop 1
	v_add_f32_dpp v130, v130, v130 row_ror:2 row_mask:0xf bank_mask:0xf
	s_nop 1
	v_add_f32_dpp v130, v130, v130 row_ror:1 row_mask:0xf bank_mask:0xf
	s_nop 1
	s_nop 0
	v_readlane_b32 s0, v130, 0
	v_readlane_b32 s1, v130, 16
	v_readlane_b32 s22, v130, 32
	v_readlane_b32 s23, v130, 48
	s_nop 1
	v_mov_b32_e32 v132, s0
	v_add_f32_e32 v132, s1, v132
	v_add_f32_e32 v132, s22, v132
	v_add_f32_e32 v132, s23, v132
	v_fmamk_f32 v132, v132, 0x3a800000, v197
	v_rsq_f32_e32 v132, v132
	s_nop 0
	v_pk_mul_f32 v[82:83], v[82:83], v[132:133] op_sel_hi:[1,0]
	v_pk_mul_f32 v[84:85], v[84:85], v[132:133] op_sel_hi:[1,0]
	v_pk_mul_f32 v[86:87], v[86:87], v[132:133] op_sel_hi:[1,0]
	v_pk_mul_f32 v[88:89], v[88:89], v[132:133] op_sel_hi:[1,0]
	v_pk_mul_f32 v[90:91], v[90:91], v[132:133] op_sel_hi:[1,0]
	v_pk_mul_f32 v[92:93], v[92:93], v[132:133] op_sel_hi:[1,0]
	v_pk_mul_f32 v[94:95], v[94:95], v[132:133] op_sel_hi:[1,0]
	v_pk_mul_f32 v[96:97], v[96:97], v[132:133] op_sel_hi:[1,0]
	v_pk_mul_f32 v[82:83], v[2:3], v[82:83]
	v_pk_mul_f32 v[84:85], v[4:5], v[84:85]
	v_pk_mul_f32 v[86:87], v[6:7], v[86:87]
	v_pk_mul_f32 v[88:89], v[8:9], v[88:89]
	v_pk_mul_f32 v[90:91], v[10:11], v[90:91]
	v_pk_mul_f32 v[92:93], v[12:13], v[92:93]
	v_pk_mul_f32 v[94:95], v[14:15], v[94:95]
	v_pk_mul_f32 v[96:97], v[16:17], v[96:97]
	v_pk_fma_f32 v[82:83], v[50:51], v[82:83], v[66:67]
	v_pk_fma_f32 v[84:85], v[52:53], v[84:85], v[68:69]
	v_pk_fma_f32 v[86:87], v[54:55], v[86:87], v[70:71]
	v_pk_fma_f32 v[88:89], v[56:57], v[88:89], v[72:73]
	v_pk_fma_f32 v[90:91], v[58:59], v[90:91], v[74:75]
	v_pk_fma_f32 v[92:93], v[60:61], v[92:93], v[76:77]
	v_pk_fma_f32 v[94:95], v[62:63], v[94:95], v[78:79]
	v_pk_fma_f32 v[96:97], v[64:65], v[96:97], v[80:81]
	v_cvt_pk_bf16_f32 v82, v82, v83
	v_cvt_pk_bf16_f32 v83, v84, v85
	v_cvt_pk_bf16_f32 v84, v86, v87
	v_cvt_pk_bf16_f32 v85, v88, v89
	v_cvt_pk_bf16_f32 v86, v90, v91
	v_cvt_pk_bf16_f32 v87, v92, v93
	v_cvt_pk_bf16_f32 v88, v94, v95
	v_cvt_pk_bf16_f32 v89, v96, v97
	global_store_dwordx2 v1, v[82:83], s[10:11] offset:0
	global_store_dwordx2 v1, v[84:85], s[10:11] offset:512
	global_store_dwordx2 v1, v[86:87], s[10:11] offset:1024
	global_store_dwordx2 v1, v[88:89], s[10:11] offset:1536
	s_add_u32 s10, s10, 0x800
	s_addc_u32 s11, s11, 0
	s_waitcnt vmcnt(24)
	v_pk_mul_f32 v[130:131], v[98:99], v[98:99]
	v_pk_fma_f32 v[130:131], v[100:101], v[100:101], v[130:131]
	v_pk_fma_f32 v[130:131], v[102:103], v[102:103], v[130:131]
	v_pk_fma_f32 v[130:131], v[104:105], v[104:105], v[130:131]
	v_pk_fma_f32 v[130:131], v[106:107], v[106:107], v[130:131]
	v_pk_fma_f32 v[130:131], v[108:109], v[108:109], v[130:131]
	v_pk_fma_f32 v[130:131], v[110:111], v[110:111], v[130:131]
	v_pk_fma_f32 v[130:131], v[112:113], v[112:113], v[130:131]
	v_add_f32_e32 v130, v130, v131
	s_nop 1
	v_add_f32_dpp v130, v130, v130 row_ror:8 row_mask:0xf bank_mask:0xf
	s_nop 1
	v_add_f32_dpp v130, v130, v130 row_ror:4 row_mask:0xf bank_mask:0xf
	s_nop 1
	v_add_f32_dpp v130, v130, v130 row_ror:2 row_mask:0xf bank_mask:0xf
	s_nop 1
	v_add_f32_dpp v130, v130, v130 row_ror:1 row_mask:0xf bank_mask:0xf
	s_nop 1
	s_nop 0
	v_readlane_b32 s0, v130, 0
	v_readlane_b32 s1, v130, 16
	v_readlane_b32 s22, v130, 32
	v_readlane_b32 s23, v130, 48
	s_nop 1
	v_mov_b32_e32 v132, s0
	v_add_f32_e32 v132, s1, v132
	v_add_f32_e32 v132, s22, v132
	v_add_f32_e32 v132, s23, v132
	v_fmamk_f32 v132, v132, 0x3a800000, v197
	v_rsq_f32_e32 v132, v132
	s_nop 0
	v_pk_mul_f32 v[98:99], v[98:99], v[132:133] op_sel_hi:[1,0]
	v_pk_mul_f32 v[100:101], v[100:101], v[132:133] op_sel_hi:[1,0]
	v_pk_mul_f32 v[102:103], v[102:103], v[132:133] op_sel_hi:[1,0]
	v_pk_mul_f32 v[104:105], v[104:105], v[132:133] op_sel_hi:[1,0]
	v_pk_mul_f32 v[106:107], v[106:107], v[132:133] op_sel_hi:[1,0]
	v_pk_mul_f32 v[108:109], v[108:109], v[132:133] op_sel_hi:[1,0]
	v_pk_mul_f32 v[110:111], v[110:111], v[132:133] op_sel_hi:[1,0]
	v_pk_mul_f32 v[112:113], v[112:113], v[132:133] op_sel_hi:[1,0]
	v_pk_mul_f32 v[98:99], v[2:3], v[98:99]
	v_pk_mul_f32 v[100:101], v[4:5], v[100:101]
	v_pk_mul_f32 v[102:103], v[6:7], v[102:103]
	v_pk_mul_f32 v[104:105], v[8:9], v[104:105]
	v_pk_mul_f32 v[106:107], v[10:11], v[106:107]
	v_pk_mul_f32 v[108:109], v[12:13], v[108:109]
	v_pk_mul_f32 v[110:111], v[14:15], v[110:111]
	v_pk_mul_f32 v[112:113], v[16:17], v[112:113]
	v_pk_fma_f32 v[98:99], v[50:51], v[98:99], v[66:67]
	v_pk_fma_f32 v[100:101], v[52:53], v[100:101], v[68:69]
	v_pk_fma_f32 v[102:103], v[54:55], v[102:103], v[70:71]
	v_pk_fma_f32 v[104:105], v[56:57], v[104:105], v[72:73]
	v_pk_fma_f32 v[106:107], v[58:59], v[106:107], v[74:75]
	v_pk_fma_f32 v[108:109], v[60:61], v[108:109], v[76:77]
	v_pk_fma_f32 v[110:111], v[62:63], v[110:111], v[78:79]
	v_pk_fma_f32 v[112:113], v[64:65], v[112:113], v[80:81]
	v_cvt_pk_bf16_f32 v98, v98, v99
	v_cvt_pk_bf16_f32 v99, v100, v101
	v_cvt_pk_bf16_f32 v100, v102, v103
	v_cvt_pk_bf16_f32 v101, v104, v105
	v_cvt_pk_bf16_f32 v102, v106, v107
	v_cvt_pk_bf16_f32 v103, v108, v109
	v_cvt_pk_bf16_f32 v104, v110, v111
	v_cvt_pk_bf16_f32 v105, v112, v113
	global_store_dwordx2 v1, v[98:99], s[10:11] offset:0
	global_store_dwordx2 v1, v[100:101], s[10:11] offset:512
	global_store_dwordx2 v1, v[102:103], s[10:11] offset:1024
	global_store_dwordx2 v1, v[104:105], s[10:11] offset:1536
	s_add_u32 s10, s10, 0x800
	s_addc_u32 s11, s11, 0
	s_waitcnt vmcnt(20)
	v_pk_mul_f32 v[130:131], v[114:115], v[114:115]
	v_pk_fma_f32 v[130:131], v[116:117], v[116:117], v[130:131]
	v_pk_fma_f32 v[130:131], v[118:119], v[118:119], v[130:131]
	v_pk_fma_f32 v[130:131], v[120:121], v[120:121], v[130:131]
	v_pk_fma_f32 v[130:131], v[122:123], v[122:123], v[130:131]
	v_pk_fma_f32 v[130:131], v[124:125], v[124:125], v[130:131]
	v_pk_fma_f32 v[130:131], v[126:127], v[126:127], v[130:131]
	v_pk_fma_f32 v[130:131], v[128:129], v[128:129], v[130:131]
	v_add_f32_e32 v130, v130, v131
	s_nop 1
	v_add_f32_dpp v130, v130, v130 row_ror:8 row_mask:0xf bank_mask:0xf
	s_nop 1
	v_add_f32_dpp v130, v130, v130 row_ror:4 row_mask:0xf bank_mask:0xf
	s_nop 1
	v_add_f32_dpp v130, v130, v130 row_ror:2 row_mask:0xf bank_mask:0xf
	s_nop 1
	v_add_f32_dpp v130, v130, v130 row_ror:1 row_mask:0xf bank_mask:0xf
	s_nop 1
	s_nop 0
	v_readlane_b32 s0, v130, 0
	v_readlane_b32 s1, v130, 16
	v_readlane_b32 s22, v130, 32
	v_readlane_b32 s23, v130, 48
	s_nop 1
	v_mov_b32_e32 v132, s0
	v_add_f32_e32 v132, s1, v132
	v_add_f32_e32 v132, s22, v132
	v_add_f32_e32 v132, s23, v132
	v_fmamk_f32 v132, v132, 0x3a800000, v197
	v_rsq_f32_e32 v132, v132
	s_nop 0
	v_pk_mul_f32 v[114:115], v[114:115], v[132:133] op_sel_hi:[1,0]
	v_pk_mul_f32 v[116:117], v[116:117], v[132:133] op_sel_hi:[1,0]
	v_pk_mul_f32 v[118:119], v[118:119], v[132:133] op_sel_hi:[1,0]
	v_pk_mul_f32 v[120:121], v[120:121], v[132:133] op_sel_hi:[1,0]
	v_pk_mul_f32 v[122:123], v[122:123], v[132:133] op_sel_hi:[1,0]
	v_pk_mul_f32 v[124:125], v[124:125], v[132:133] op_sel_hi:[1,0]
	v_pk_mul_f32 v[126:127], v[126:127], v[132:133] op_sel_hi:[1,0]
	v_pk_mul_f32 v[128:129], v[128:129], v[132:133] op_sel_hi:[1,0]
	v_pk_mul_f32 v[114:115], v[2:3], v[114:115]
	v_pk_mul_f32 v[116:117], v[4:5], v[116:117]
	v_pk_mul_f32 v[118:119], v[6:7], v[118:119]
	v_pk_mul_f32 v[120:121], v[8:9], v[120:121]
	v_pk_mul_f32 v[122:123], v[10:11], v[122:123]
	v_pk_mul_f32 v[124:125], v[12:13], v[124:125]
	v_pk_mul_f32 v[126:127], v[14:15], v[126:127]
	v_pk_mul_f32 v[128:129], v[16:17], v[128:129]
	v_pk_fma_f32 v[114:115], v[50:51], v[114:115], v[66:67]
	v_pk_fma_f32 v[116:117], v[52:53], v[116:117], v[68:69]
	v_pk_fma_f32 v[118:119], v[54:55], v[118:119], v[70:71]
	v_pk_fma_f32 v[120:121], v[56:57], v[120:121], v[72:73]
	v_pk_fma_f32 v[122:123], v[58:59], v[122:123], v[74:75]
	v_pk_fma_f32 v[124:125], v[60:61], v[124:125], v[76:77]
	v_pk_fma_f32 v[126:127], v[62:63], v[126:127], v[78:79]
	v_pk_fma_f32 v[128:129], v[64:65], v[128:129], v[80:81]
	v_cvt_pk_bf16_f32 v114, v114, v115
	v_cvt_pk_bf16_f32 v115, v116, v117
	v_cvt_pk_bf16_f32 v116, v118, v119
	v_cvt_pk_bf16_f32 v117, v120, v121
	v_cvt_pk_bf16_f32 v118, v122, v123
	v_cvt_pk_bf16_f32 v119, v124, v125
	v_cvt_pk_bf16_f32 v120, v126, v127
	v_cvt_pk_bf16_f32 v121, v128, v129
	global_store_dwordx2 v1, v[114:115], s[10:11] offset:0
	global_store_dwordx2 v1, v[116:117], s[10:11] offset:512
	global_store_dwordx2 v1, v[118:119], s[10:11] offset:1024
	global_store_dwordx2 v1, v[120:121], s[10:11] offset:1536
	s_branch .Lrn_p3_end
